# diff attention: next step's first four K-fragment LDS reads issued right behind the per-step barrier into free registers (covered by the last PV MFMA, row-sum tail and scalar loop head)
# baseline (speedup 1.0000x reference)
; template <bool HAS_QK, bool HAS_PV> ...
;     ...
;     if (HAS_PV) {
; #pragma unroll
;         for (int ks = 2; ks < 4; ++ks)
; #pragma unroll
;             for (int c4 = 0; c4 < 4; ++c4) { const bf16x8 vf = vfrag(Vp, vb0, vb1, ks, c4); O[c4] = __builtin_amdgcn_mfma_f32_32x32x16_bf16(vf, P[ks], O[c4], 0, 0, 0); }
;     }
;     if (HAS_QK) {
;         float sum0 = 0.f, sum1 = 0.f;
; #pragma unroll
;         for (int r = 0; r < 16; ++r) { s0[r] = __builtin_amdgcn_exp2f(s0[r]); s1[r] = __builtin_amdgcn_exp2f(s1[r]); sum0 += s0[r]; sum1 += s1[r]; }
; #pragma unroll
;         for (int sp = 0; sp < 2; ++sp) {
;             u32x4 w0, w1;
;             w0.x = cvtpk(s0[8 * sp + 0], s0[8 * sp + 1]); w0.y = cvtpk(s0[8 * sp + 2], s0[8 * sp + 3]); w0.z = cvtpk(s0[8 * sp + 4], s0[8 * sp + 5]); w0.w = cvtpk(s0[8 * sp + 6], s0[8 * sp + 7]);
;             w1.x = cvtpk(s1[8 * sp + 0], s1[8 * sp + 1]); w1.y = cvtpk(s1[8 * sp + 2], s1[8 * sp + 3]); w1.z = cvtpk(s1[8 * sp + 4], s1[8 * sp + 5]); w1.w = cvtpk(s1[8 * sp + 6], s1[8 * sp + 7]);
;             P[sp] = __builtin_bit_cast(bf16x8, w0); P[2 + sp] = __builtin_bit_cast(bf16x8, w1);
;         }
;         if (need && !first) {
; #pragma unroll
;             for (int e = 0; e < 4; ++e) O[e] *= f;
;         }
;         lrun = lrun * f + (sum0 + sum1);
;     }
; }
;     ...
;     for (int st = 0; st < ns; ++st) {
;         const unsigned bb = (st & 1) * 65536u;
;         if (st + 1 < ns) DIFF_DMA2(st + 1, ((st + 1) & 1) * 65536u);
;         const LAS unsigned char* KA = lds + bb + cmap * 1024; const LAS unsigned char* VA = lds + bb + 16384;
;         const LAS unsigned char* KB = lds + bb + 32768 + cmap * 1024; const LAS unsigned char* VB = lds + bb + 49152;
;         { const int kq = st * 128;
;           const bool farR = (kq - q0w - 31 >= 91), farL = (kq + 63 - q0w <= -91), nr = !(farR || farL);
;           diff_step<true, false>(KA, VA, tab, qf, O, P, mrun, lrun, nr ? 0.f : (farR ? tab[256] : tab[0]), kq + ibq, kb0, kb1, vb0, vb1, nr, st == 0); }
;         { const int kq = st * 128 + 64;
;           const bool farR = (kq - q0w - 31 >= 91), farL = (kq + 63 - q0w <= -91), nr = !(farR || farL);
;           diff_step<true, true>(KB, VA, tab, qf, O, P, mrun, lrun, nr ? 0.f : (farR ? tab[256] : tab[0]), kq + ibq, kb0, kb1, vb0, vb1, nr); }
;         diff_step<false, true>(KB, VB, tab, qf, O, P, mrun, lrun, 0.f, 0, kb0, kb1, vb0, vb1, false);
.LBB0_200:
	s_add_i32 s10, s34, 0xffff0000
	s_and_b32 s10, s10, 0x10000
	s_add_i32 s36, s10, 0
	s_add_i32 s10, s36, s27
	v_add_u32_e32 v248, s10, v172
	v_add_u32_e32 v249, s10, v175
	v_add_u32_e32 v237, s36, v173
	v_add_u32_e32 v236, s36, v174
	ds_read_b128 v[2:5], v248
	ds_read_b128 v[6:9], v248 offset:8192
	ds_read_b128 v[10:13], v249
	ds_read_b128 v[182:185], v249 offset:8192
	s_branch .LBB0_202
.LBB0_199:
	ds_read_b64_tr_b16 v[220:221], v237 offset:49152
	ds_read_b64_tr_b16 v[222:223], v236 offset:51200
	ds_read_b64_tr_b16 v[224:225], v237 offset:49664
	ds_read_b64_tr_b16 v[226:227], v236 offset:51712
	ds_read_b64_tr_b16 v[228:229], v237 offset:50176
	ds_read_b64_tr_b16 v[230:231], v236 offset:52224
	ds_read_b64_tr_b16 v[232:233], v237 offset:50688
	ds_read_b64_tr_b16 v[234:235], v236 offset:52736
	s_waitcnt lgkmcnt(6)
	v_mfma_f32_32x32x16_bf16 v[64:79], v[220:223], v[182:185], v[64:79]
	ds_read_b64_tr_b16 v[220:221], v237 offset:53248
	ds_read_b64_tr_b16 v[222:223], v236 offset:55296
	v_cvt_pk_bf16_f32 v186, v120, v121
	v_cvt_pk_bf16_f32 v187, v122, v123
	v_cvt_pk_bf16_f32 v188, v124, v125
	v_cvt_pk_bf16_f32 v189, v126, v127
	v_exp_f32_e32 v96, v96
	v_exp_f32_e32 v97, v97
	s_waitcnt lgkmcnt(6)
	v_mfma_f32_32x32x16_bf16 v[48:63], v[224:227], v[182:185], v[48:63]
	ds_read_b64_tr_b16 v[224:225], v237 offset:53760
	ds_read_b64_tr_b16 v[226:227], v236 offset:55808
	v_exp_f32_e32 v98, v98
	v_exp_f32_e32 v99, v99
	v_exp_f32_e32 v100, v100
	s_waitcnt lgkmcnt(6)
	v_mfma_f32_32x32x16_bf16 v[32:47], v[228:231], v[182:185], v[32:47]
	ds_read_b64_tr_b16 v[228:229], v237 offset:54272
	ds_read_b64_tr_b16 v[230:231], v236 offset:56320
	v_exp_f32_e32 v101, v101
	v_exp_f32_e32 v102, v102
	v_exp_f32_e32 v103, v103
	v_cvt_pk_bf16_f32 v10, v96, v97
	v_cvt_pk_bf16_f32 v11, v98, v99
	s_waitcnt lgkmcnt(6)
	v_mfma_f32_32x32x16_bf16 v[16:31], v[232:235], v[182:185], v[16:31]
	ds_read_b64_tr_b16 v[232:233], v237 offset:54784
	ds_read_b64_tr_b16 v[234:235], v236 offset:56832
	v_cvt_pk_bf16_f32 v12, v100, v101
	v_cvt_pk_bf16_f32 v13, v102, v103
	v_exp_f32_e32 v104, v104
	v_exp_f32_e32 v105, v105
	v_exp_f32_e32 v106, v106
	s_waitcnt lgkmcnt(6)
	v_mfma_f32_32x32x16_bf16 v[64:79], v[220:223], v[186:189], v[64:79]
	ds_read_b64_tr_b16 v[220:221], v237 offset:57344
	ds_read_b64_tr_b16 v[222:223], v236 offset:59392
	v_exp_f32_e32 v107, v107
	v_exp_f32_e32 v108, v108
	v_exp_f32_e32 v109, v109
	s_waitcnt lgkmcnt(6)
	v_mfma_f32_32x32x16_bf16 v[48:63], v[224:227], v[186:189], v[48:63]
	ds_read_b64_tr_b16 v[224:225], v237 offset:57856
	ds_read_b64_tr_b16 v[226:227], v236 offset:59904
	v_exp_f32_e32 v110, v110
	v_exp_f32_e32 v111, v111
	v_cvt_pk_bf16_f32 v216, v104, v105
	v_cvt_pk_bf16_f32 v217, v106, v107
	v_cvt_pk_bf16_f32 v218, v108, v109
	v_cvt_pk_bf16_f32 v219, v110, v111
	s_waitcnt lgkmcnt(6)
	v_mfma_f32_32x32x16_bf16 v[32:47], v[228:231], v[186:189], v[32:47]
	ds_read_b64_tr_b16 v[228:229], v237 offset:58368
	ds_read_b64_tr_b16 v[230:231], v236 offset:60416
	v_add_f32_e32 v210, v179, v180
	v_add_f32_e32 v211, v80, v81
	v_add_f32_e32 v212, v112, v113
	v_add_f32_e32 v213, v96, v97
	v_add_f32_e32 v210, v130, v210
	v_add_f32_e32 v211, v82, v211
	v_add_f32_e32 v212, v114, v212
	s_waitcnt lgkmcnt(6)
	v_mfma_f32_32x32x16_bf16 v[16:31], v[232:235], v[186:189], v[16:31]
	ds_read_b64_tr_b16 v[232:233], v237 offset:58880
	ds_read_b64_tr_b16 v[234:235], v236 offset:60928
	v_add_f32_e32 v213, v98, v213
	v_add_f32_e32 v210, v131, v210
	v_add_f32_e32 v211, v83, v211
	v_add_f32_e32 v212, v115, v212
	v_add_f32_e32 v213, v99, v213
	v_add_f32_e32 v210, v132, v210
	v_add_f32_e32 v211, v84, v211
	v_add_f32_e32 v212, v116, v212
	s_waitcnt lgkmcnt(6)
	v_mfma_f32_32x32x16_bf16 v[64:79], v[220:223], v[10:13], v[64:79]
	ds_read_b64_tr_b16 v[220:221], v237 offset:61440
	ds_read_b64_tr_b16 v[222:223], v236 offset:63488
	v_add_f32_e32 v213, v100, v213
	v_add_f32_e32 v210, v133, v210
	v_add_f32_e32 v211, v85, v211
	v_add_f32_e32 v212, v117, v212
	v_add_f32_e32 v213, v101, v213
	v_add_f32_e32 v210, v134, v210
	v_add_f32_e32 v211, v86, v211
	s_waitcnt lgkmcnt(6)
	v_mfma_f32_32x32x16_bf16 v[48:63], v[224:227], v[10:13], v[48:63]
	ds_read_b64_tr_b16 v[224:225], v237 offset:61952
	ds_read_b64_tr_b16 v[226:227], v236 offset:64000
	v_add_f32_e32 v212, v118, v212
	v_add_f32_e32 v213, v102, v213
	v_add_f32_e32 v210, v135, v210
	v_add_f32_e32 v211, v87, v211
	v_add_f32_e32 v212, v119, v212
	v_add_f32_e32 v213, v103, v213
	v_add_f32_e32 v210, v136, v210
	s_waitcnt lgkmcnt(6)
	v_mfma_f32_32x32x16_bf16 v[32:47], v[228:231], v[10:13], v[32:47]
	ds_read_b64_tr_b16 v[228:229], v237 offset:62464
	ds_read_b64_tr_b16 v[230:231], v236 offset:64512
	v_add_f32_e32 v211, v88, v211
	v_add_f32_e32 v212, v120, v212
	v_add_f32_e32 v213, v104, v213
	v_add_f32_e32 v210, v137, v210
	v_add_f32_e32 v211, v89, v211
	v_add_f32_e32 v212, v121, v212
	v_add_f32_e32 v213, v105, v213
	v_add_f32_e32 v210, v138, v210
	s_waitcnt lgkmcnt(6)
	v_mfma_f32_32x32x16_bf16 v[16:31], v[232:235], v[10:13], v[16:31]
	ds_read_b64_tr_b16 v[232:233], v237 offset:62976
	ds_read_b64_tr_b16 v[234:235], v236 offset:65024
	v_add_f32_e32 v211, v90, v211
	v_add_f32_e32 v212, v122, v212
	v_add_f32_e32 v213, v106, v213
	v_add_f32_e32 v210, v139, v210
	v_add_f32_e32 v211, v91, v211
	v_add_f32_e32 v212, v123, v212
	v_add_f32_e32 v213, v107, v213
	s_waitcnt lgkmcnt(6)
	v_mfma_f32_32x32x16_bf16 v[64:79], v[220:223], v[216:219], v[64:79]
	v_add_f32_e32 v210, v140, v210
	v_add_f32_e32 v211, v92, v211
	v_add_f32_e32 v212, v124, v212
	v_add_f32_e32 v213, v108, v213
	v_add_f32_e32 v210, v141, v210
	v_add_f32_e32 v211, v93, v211
	v_add_f32_e32 v212, v125, v212
	s_waitcnt lgkmcnt(4)
	v_mfma_f32_32x32x16_bf16 v[48:63], v[224:227], v[216:219], v[48:63]
	v_add_f32_e32 v213, v109, v213
	v_add_f32_e32 v210, v142, v210
	v_add_f32_e32 v211, v94, v211
	v_add_f32_e32 v212, v126, v212
	v_add_f32_e32 v213, v110, v213
	v_add_f32_e32 v210, v143, v210
	v_add_f32_e32 v211, v95, v211
	v_add_f32_e32 v212, v127, v212
	s_waitcnt lgkmcnt(2)
	v_mfma_f32_32x32x16_bf16 v[32:47], v[228:231], v[216:219], v[32:47]
	s_waitcnt vmcnt(0) lgkmcnt(0)
	s_barrier
	s_addk_i32 s29, 0x80
	s_add_i32 s34, s34, 0x10000
	s_add_i32 s35, s35, 1
	s_cmp_eq_u32 s31, s29
	s_cbranch_scc1 .Ldiff_noprefetch
	s_add_i32 s10, s34, 0xffff0000
	s_and_b32 s10, s10, 0x10000
	s_add_i32 s36, s10, 0
	s_add_i32 s10, s36, s27
	v_add_u32_e32 v248, s10, v172
	v_add_u32_e32 v249, s10, v175
	v_add_u32_e32 v237, s36, v173
	v_add_u32_e32 v236, s36, v174
	ds_read_b128 v[2:5], v248
	ds_read_b128 v[6:9], v248 offset:8192
	ds_read_b128 v[10:13], v249
	ds_read_b128 v[182:185], v249 offset:8192
.Ldiff_noprefetch:
	v_mfma_f32_32x32x16_bf16 v[16:31], v[232:235], v[216:219], v[16:31]
	v_add_f32_e32 v213, v111, v213
	v_add_f32_e32 v210, v210, v211
	v_add_f32_e32 v212, v212, v213
	v_fmac_f32_e32 v210, v178, v0
	v_fma_f32 v178, v210, v14, v212
	s_cmp_eq_u32 s31, s29
	s_cbranch_scc1 .LBB0_227

; template <bool HAS_QK, bool HAS_PV> ...
;     ...
;     if (HAS_QK) {
;         const float c0 = beta - mrun;
; #pragma unroll
;         for (int r = 0; r < 16; ++r) { s0[r] = c0; s1[r] = c0; }
; #pragma unroll
;         for (int s4 = 0; s4 < 4; ++s4) {
;             const bf16x8 a0 = KFRAG(Kt, kb0, kb1, 0, 0, s4), a1 = KFRAG(Kt, kb0, kb1, 1, 0, s4);
;             s0 = __builtin_amdgcn_mfma_f32_32x32x16_bf16(a0, qf[s4], s0, 0, 0, 0);
;             s1 = __builtin_amdgcn_mfma_f32_32x32x16_bf16(a1, qf[s4], s1, 0, 0, 0);
;         }
.Lcreg_ok_a:
	s_andn2_b64 vcc, exec, s[4:5]
	v_mfma_f32_32x32x16_bf16 v[128:143], v[2:5], v[144:147], v[194:209]
	ds_read_b128 v[220:223], v248 offset:512
	v_mfma_f32_32x32x16_bf16 v[80:95], v[6:9], v[144:147], v[194:209]
	ds_read_b128 v[224:227], v248 offset:8704
	v_mfma_f32_32x32x16_bf16 v[128:143], v[10:13], v[148:151], v[128:143]
	ds_read_b128 v[228:231], v249 offset:512
	v_mfma_f32_32x32x16_bf16 v[80:95], v[182:185], v[148:151], v[80:95]
	ds_read_b128 v[232:235], v249 offset:8704
	s_waitcnt lgkmcnt(3)
	v_mfma_f32_32x32x16_bf16 v[128:143], v[220:223], v[152:155], v[128:143]
	s_waitcnt lgkmcnt(2)
	v_mfma_f32_32x32x16_bf16 v[80:95], v[224:227], v[152:155], v[80:95]
	s_waitcnt lgkmcnt(1)
	v_mfma_f32_32x32x16_bf16 v[128:143], v[228:231], v[156:159], v[128:143]
	s_waitcnt lgkmcnt(0)
	v_mfma_f32_32x32x16_bf16 v[80:95], v[232:235], v[156:159], v[80:95]
	ds_read_b128 v[220:223], v248 offset:32768
	ds_read_b128 v[224:227], v249 offset:32768
	ds_read_b128 v[228:231], v248 offset:33280
	ds_read_b128 v[232:235], v249 offset:33280
	s_cmp_ge_u32 s35, s17
	s_cbranch_scc1 .Ldiff_nodma
	s_and_b32 s4, s34, 0x10000
	s_add_i32 s4, s24, s4
	v_readlane_b32 s10, v247, 0
	v_readlane_b32 s11, v247, 1
	s_add_i32 s56, s29, 0x80
	s_lshl_b32 s56, s56, 10
	s_add_u32 s10, s10, s56
	s_addc_u32 s11, s11, 0
	s_add_u32 s56, s10, s72
	s_addc_u32 s57, s11, s73
	s_mov_b32 m0, s4
	s_nop 0
	global_load_lds_dwordx4 v250, s[56:57]
	s_add_i32 m0, s4, 0x2000
	s_nop 0
	global_load_lds_dwordx4 v251, s[56:57]
	s_add_u32 s56, s10, s74
	s_addc_u32 s57, s11, s75
	s_add_i32 m0, s4, 0x4000
	s_nop 0
	global_load_lds_dwordx4 v250, s[56:57]
	s_add_i32 m0, s4, 0x6000
	s_nop 0
	global_load_lds_dwordx4 v251, s[56:57]
	s_add_u32 s56, s10, s68
	s_addc_u32 s57, s11, s69
	s_add_i32 m0, s4, 0x8000
	s_nop 0
	global_load_lds_dwordx4 v250, s[56:57]
	s_add_i32 m0, s4, 0xa000
	s_nop 0
	global_load_lds_dwordx4 v251, s[56:57]
	s_add_u32 s56, s10, s96
	s_addc_u32 s57, s11, s97
	s_add_i32 m0, s4, 0xc000
	s_nop 0
	global_load_lds_dwordx4 v250, s[56:57]
	s_add_i32 m0, s4, 0xe000
	s_nop 0
	global_load_lds_dwordx4 v251, s[56:57]
	s_branch .Ldiff_dma_done
